# speedup vs baseline: 1.0139x; 1.0139x over previous
; __device__ __forceinline__ void ssm_state_item(KP P, int g, int cbase, unsigned char* lds) {
;     const bf16_t* proj = (const bf16_t*)(P->ws + OFF_RA); float* S = (float*)(P->ws + OFF_S);
;     const int tid = threadIdx.x, wid = tid >> 6, lane = tid & 63, cb = cbase + wid;
;     const int n = cb * 16 + (lane & 15), q = lane >> 4;
;     const bf16_t* xbase = proj + (size_t)(n * 32 + (q >> 1)) * 4096 + g * 16 + 8 * (q & 1);
;     bf16x8 X[16];
; #pragma unroll
;     for (int i = 0; i < 16; ++i) X[i] = *(const bf16x8*)(xbase + (size_t)(2 * i) * 4096);
;     const u32x4* at = (const u32x4*)(P->ws + OFF_AS) + (size_t)g * 256 * 64 + lane;
;     u32x4* stage = (u32x4*)lds;
; __global__ void __launch_bounds__(512, 2) mega(Params Parg) {
;     ...
;         for (int it = blk; it < 256; it += G) ssm_state_item(P, it >> 2, (it & 3) * 8, shm);
.LBB0_999:
	s_or_b64 exec, exec, s[6:7]
	s_waitcnt lgkmcnt(0)
	s_barrier
	s_cmpk_lt_i32 s2, 0x100
	s_mov_b64 s[6:7], s[0:1]
	v_mov_b32_e32 v97, v204
	s_cselect_b64 s[10:11], -1, 0
	s_cmpk_gt_i32 s2, 0xff
	v_lshrrev_b32_e32 v164, 6, v204
	v_and_b32_e32 v96, 63, v204
	v_and_b32_e32 v166, 15, v204
	v_and_b32_e32 v110, 48, v204
	s_cbranch_scc1 .LBB0_1006
	s_load_dwordx2 s[12:13], s[6:7], 0x118
	v_mov_b32_e32 v99, 0
	v_mov_b32_e32 v165, v99
	v_lshlrev_b32_e32 v1, 4, v96
	v_lshlrev_b64 v[2:3], 13, v[164:165]
	v_lshrrev_b32_e32 v0, 1, v204
	s_waitcnt lgkmcnt(0)
	s_add_u32 s8, s12, 0xc8c0000
	v_or_b32_e32 v2, v2, v1
	v_mov_b32_e32 v111, v99
	v_and_b32_e32 v0, 8, v0
	s_addc_u32 s9, s13, 0
	v_add_u32_e32 v113, 0, v1
	v_lshl_add_u64 v[100:101], s[12:13], 0, v[2:3]
	v_lshl_add_u64 v[2:3], s[12:13], 0, v[110:111]
	s_mov_b64 s[12:13], 0x174c0080
	v_bfe_u32 v112, v204, 5, 1
	v_lshl_add_u32 v114, v164, 13, v113
	v_lshl_add_u64 v[102:103], v[2:3], 0, s[12:13]
	v_lshl_or_b32 v111, v164, 4, v166
	v_lshlrev_b32_e32 v115, 5, v166
	v_lshlrev_b32_e32 v104, 1, v0
	v_mov_b32_e32 v105, v99
	s_movk_i32 s18, 0x4000
	s_mov_b32 s19, 0x8000
	s_mov_b32 s25, 0xc000
	s_mov_b32 s30, 0x10000
	s_mov_b32 s31, 0x14000
	s_mov_b32 s33, 0x18000
	s_mov_b32 s34, 0x1c000
	s_mov_b32 s35, 0x20000
	s_mov_b32 s36, 0x24000
	s_mov_b32 s37, 0x28000
	s_mov_b32 s38, 0x2c000
	s_mov_b32 s39, 0x30000
	s_mov_b32 s40, 0x34000
	s_mov_b64 s[12:13], 0x100
	s_mov_b32 s42, s2
	s_cmpk_lg_i32 s20, 0x100
	s_cbranch_scc1 .Lmy_noperm5
	s_and_b32 s14, s2, 7
	s_lshr_b32 s42, s2, 3
	s_and_b32 s41, s42, 15
	s_lshr_b32 s42, s42, 4
	s_lshl_b32 s42, s42, 3
	s_or_b32 s42, s42, s14
	s_lshl_b32 s42, s42, 4
	s_or_b32 s42, s42, s41
.Lmy_noperm5:
	s_lshl_b32 s41, s42, 3
	s_branch .LBB0_1002

; __global__ void __launch_bounds__(512, 2) mega(Params Parg) {
;     ...
;         PHASE_VARS
;         unsigned* ctr = WSP(unsigned, OFF_CTR);
;         volatile int* slot = (volatile int*)(shm + 35840);
;         for (;;) {
;             if (tid == 0) *slot = (int)atomicAdd(ctr, 1u);
;             __syncthreads();
;             const int it = *slot;
;             __syncthreads();
;             if (it >= 48 + 1536) break;
.LBB0_1078:
	s_or_b64 exec, exec, s[6:7]
	s_mov_b64 s[30:31], s[0:1]
	s_waitcnt lgkmcnt(0)
	v_mov_b32_e32 v0, v204
	s_barrier
	s_load_dwordx2 s[34:35], s[30:31], 0x118
	v_and_b32_e32 v12, 63, v0
	v_ashrrev_i32_e32 v99, 6, v0
	v_cmp_eq_u32_e64 s[6:7], 0, v0
	v_lshrrev_b32_e32 v0, 2, v204
	s_waitcnt lgkmcnt(0)
	s_add_u32 s36, s34, 0x1d230000
	v_and_b32_e32 v2, 0xf0, v0
	v_and_b32_e32 v101, 0xfc, v0
	v_or_b32_e32 v133, 3, v0
	v_lshlrev_b32_e32 v0, 3, v204
	s_addc_u32 s37, s35, 0
	v_and_b32_e32 v100, 0x78, v0
	s_add_u32 s38, s34, 0xc8c0000
	v_lshrrev_b32_e32 v135, 4, v204
	v_mul_u32_u24_e32 v1, 0x88, v100
	v_bfe_u32 v97, v204, 4, 2
	s_addc_u32 s39, s35, 0
	v_mov_b32_e32 v103, 0
	v_lshlrev_b32_e32 v0, 1, v135
	v_lshlrev_b32_e32 v1, 1, v1
	v_lshlrev_b32_e32 v102, 4, v97
	v_add3_u32 v136, 0, v0, v1
	v_add3_u32 v137, 0, v1, v0
	v_lshl_add_u64 v[0:1], s[34:35], 0, v[102:103]
	s_mov_b64 s[8:9], 0x4800000
	s_add_u32 s40, s34, 0x6840000
	v_lshl_add_u64 v[104:105], v[0:1], 0, s[8:9]
	s_addc_u32 s41, s35, 0
	v_mov_b32_e32 v0, 0xfffffa00
	s_add_i32 s71, 0, 0x10000
	v_add_u32_e32 v13, 0, v102
	v_lshl_or_b32 v143, v164, 4, v0
	s_movk_i32 s8, 0x2100
	v_mov_b32_e32 v0, s71
	v_lshlrev_b32_e32 v102, 4, v96
	v_mad_u32_u24 v15, v164, s8, v0
	v_lshl_add_u64 v[0:1], s[34:35], 0, v[102:103]
	s_mov_b64 s[8:9], 0x1d233700
	v_lshl_add_u64 v[106:107], v[0:1], 0, s[8:9]
	s_mov_b64 s[8:9], 0x1d3b3700
	v_lshl_add_u64 v[108:109], v[0:1], 0, s[8:9]
	v_lshlrev_b32_e32 v0, 1, v166
	v_mul_u32_u24_e32 v1, 0x840, v97
	v_add3_u32 v144, v15, v0, v1
	v_mul_u32_u24_e32 v0, 0x210, v166
	v_add3_u32 v145, v15, v0, v110
	v_and_b32_e32 v15, 1, v99
	v_add_u32_e32 v165, 0, v102
	v_lshlrev_b32_e32 v102, 9, v15
	v_lshl_add_u64 v[0:1], s[34:35], 0, v[102:103]
	v_lshlrev_b32_e32 v102, 3, v12
	v_lshl_add_u64 v[0:1], v[0:1], 0, v[102:103]
	s_mov_b64 s[12:13], 0x174c0000
	v_lshlrev_b32_e32 v102, 2, v12
	v_or_b32_e32 v141, v2, v166
	v_lshl_or_b32 v142, v97, 2, v2
	v_lshlrev_b32_e32 v2, 9, v164
	v_lshl_add_u64 v[110:111], v[0:1], 0, s[12:13]
	v_lshl_add_u64 v[0:1], s[34:35], 0, v[102:103]
	s_mov_b64 s[12:13], 0x194c0000
	v_lshlrev_b32_e32 v102, 3, v135
	s_mov_b64 s[18:19], src_shared_base
	v_or_b32_e32 v129, 1, v101
	v_or_b32_e32 v131, 2, v101
	v_mul_u32_u24_e32 v14, 0x110, v166
	v_mov_b32_e32 v3, v103
	v_or_b32_e32 v4, 0x100, v2
	v_mov_b32_e32 v5, v103
	v_or_b32_e32 v6, 0x140, v2
	v_mov_b32_e32 v7, v103
	v_or_b32_e32 v8, 0x180, v2
	v_mov_b32_e32 v9, v103
	v_or_b32_e32 v10, 0x1c0, v2
	v_mov_b32_e32 v11, v103
	s_add_u32 s42, s34, 0x148c0000
	v_lshl_add_u64 v[112:113], v[0:1], 0, s[12:13]
	v_lshl_add_u64 v[0:1], s[34:35], 0, v[102:103]
	s_mov_b64 s[12:13], 0x1d210000
	v_lshlrev_b32_e32 v128, 3, v101
	v_lshlrev_b32_e32 v130, 3, v129
	v_lshlrev_b32_e32 v132, 3, v131
	v_lshlrev_b32_e32 v134, 3, v133
	v_add_u32_e32 v138, 32, v135
	v_or_b32_e32 v139, 64, v135
	v_add_u32_e32 v140, 0x60, v135
	s_mov_b32 s18, 0x10000
	v_lshlrev_b32_e32 v98, 3, v97
	s_addc_u32 s43, s35, 0
	v_lshl_add_u32 v167, v164, 13, v165
	v_lshlrev_b32_e32 v146, 8, v97
	v_cmp_eq_u32_e64 s[8:9], 0, v15
	v_lshlrev_b32_e32 v147, 7, v15
	v_or_b32_e32 v148, 64, v166
	v_or_b32_e32 v149, 0x80, v166
	v_or_b32_e32 v150, 0xc0, v166
	v_lshl_or_b32 v151, v15, 12, v12
	v_lshl_add_u64 v[114:115], v[0:1], 0, s[12:13]
	s_mov_b64 s[44:45], 0
	s_add_i32 s25, 0, 0x8c00
	s_movk_i32 s56, 0x630
	s_movk_i32 s57, 0x22f
	s_movk_i32 s58, 0x1000
	v_add_u32_e32 v152, v13, v14
	s_movk_i32 s59, 0x2000
	s_movk_i32 s60, 0xfff
	s_mov_b64 s[46:47], 0xc8c1800
	s_mov_b32 s61, 0xc8c1000
	v_lshlrev_b64 v[116:117], 4, v[2:3]
	v_lshlrev_b64 v[118:119], 4, v[4:5]
	v_lshlrev_b64 v[120:121], 4, v[6:7]
	v_lshlrev_b64 v[122:123], 4, v[8:9]
	v_lshlrev_b64 v[124:125], 4, v[10:11]
	s_mov_b32 s62, 0x11000
	v_mbcnt_hi_u32_b32 v205, -1, v168
	s_mov_b32 s63, 0x1fc0000
	s_movk_i32 s64, 0x3c00
	s_movk_i32 s65, 0x7f
	s_mov_b32 s66, 0x1c8c0000
	v_mov_b32_e32 v153, 0x100
	v_mov_b32_e32 v154, 0x80
	s_and_saveexec_b64 s[100:101], s[6:7]
	s_cbranch_execz .Lmy_deq_skip0
	v_mov_b32_e32 v232, 1
	global_atomic_add v232, v103, v232, s[36:37] sc0
.Lmy_deq_skip0:
	s_or_b64 exec, exec, s[100:101]
	s_branch .LBB0_1081

; __global__ void __launch_bounds__(512, 2) mega(Params Parg) {
;     ...
;         for (;;) {
;             if (tid == 0) *slot = (int)atomicAdd(ctr, 1u);
;             __syncthreads();
.LBB0_1081:
	s_and_saveexec_b64 s[12:13], s[6:7]
	s_cbranch_execz .LBB0_1085
	s_mov_b64 s[48:49], exec
	v_mbcnt_lo_u32_b32 v0, s48, 0
	v_mbcnt_hi_u32_b32 v0, s49, v0
	v_cmp_eq_u32_e32 vcc, 0, v0
	s_and_saveexec_b64 s[14:15], vcc
	s_cbranch_execz .LBB0_1084
	s_waitcnt vmcnt(0)
	v_mov_b32_e32 v1, v232

; __device__ __forceinline__ bf16_t f2bf(float v) { return (bf16_t)(cvt_pk_bf16(v, 0.f) & 0xffffu); }
; __device__ __forceinline__ float bflo(unsigned w) { return __uint_as_float(w << 16); }
; __device__ __forceinline__ float bfhi(unsigned w) { return __uint_as_float(w & 0xffff0000u); }
; __device__ __forceinline__ void gmlp_item(KP P, int ch, int h, unsigned char* lds) {
;     ...
;     const int t = threadIdx.x, w = t >> 6, lane = t & 63, r0 = ch * 128;
;     bf16_t uu16[8][4]; float bsv[4];
; #pragma unroll
;     for (int reg = 0; reg < 4; ++reg) {
;         const int tt = 16 * w + (lane >> 4) * 4 + reg;
;         bsv[reg] = bs[tt * 8 + h];
; #pragma unroll
;         for (int db = 0; db < 8; ++db) uu16[db][reg] = proj[(size_t)(r0 + tt) * 4096 + 1024 + h * 128 + db * 16 + (lane & 15)];
;     }
;     {
;         const int d0 = (t & 15) * 8;
;         float gg[8], bb[8];
; #pragma unroll
;         for (int j = 0; j < 8; ++j) { gg[j] = lng[h * 128 + d0 + j]; bb[j] = lnb[h * 128 + d0 + j]; }
; #pragma unroll
;         for (int i = 0; i < 4; ++i) {
;             const int s = (t >> 4) + 32 * i;
;             const u32x4 x = *(const u32x4*)(proj + (size_t)(r0 + s) * 4096 + 2048 + h * 128 + d0);
;             const f32x2 st = stats[s];
; #pragma unroll
;             for (int j = 0; j < 4; ++j) {
;                 T[(d0 + 2 * j) * 136 + s] = f2bf((bflo(x[j]) - st.x) * st.y * gg[2 * j] + bb[2 * j]);
;                 T[(d0 + 2 * j + 1) * 136 + s] = f2bf((bfhi(x[j]) - st.x) * st.y * gg[2 * j + 1] + bb[2 * j + 1]);
;             }
;         }
;     }
; __global__ void __launch_bounds__(512, 2) mega(Params Parg) {
;     ...
;             if (tid == 0) *slot = (int)atomicAdd(ctr, 1u);
;             __syncthreads();
;             const int it = *slot;
;             __syncthreads();
;             if (it >= 48 + 1536) break;
;             if (it < 48) ssm_scan_wave(P, it * 8 + wid, lane);
;             else if (it < 560) { const int a = it - 48; attn_item(P, a >> 2, a & 3, shm); }
;             else { const int b = it - 560; gmlp_item(P, b >> 3, b & 7, shm); }
.LBB0_1085:
	s_or_b64 exec, exec, s[12:13]
	s_cmp_lg_u32 s25, -1
	s_cselect_b32 s12, s25, 0
	s_cselect_b32 s13, s19, 0
	v_mov_b32_e32 v0, s12
	v_mov_b32_e32 v1, s13
	s_waitcnt lgkmcnt(0)
	s_barrier
	flat_load_dword v0, v[0:1] sc0 sc1
	s_waitcnt vmcnt(0)
	s_mov_b64 s[12:13], -1
	s_waitcnt lgkmcnt(0)
	s_barrier
	s_and_saveexec_b64 s[100:101], s[6:7]
	s_cbranch_execz .Lmy_deq_skip1
	v_mov_b32_e32 v232, 1
	global_atomic_add v232, v103, v232, s[36:37] sc0
.Lmy_deq_skip1:
	s_or_b64 exec, exec, s[100:101]
	v_cmp_gt_i32_e32 vcc, s56, v0
	s_and_saveexec_b64 s[48:49], vcc
	s_cbranch_execz .LBB0_1080
	v_cmp_lt_i32_e32 vcc, 47, v0
	s_and_saveexec_b64 s[12:13], vcc
	s_xor_b64 s[50:51], exec, s[12:13]
	s_cbranch_execz .LBB0_1092
	v_cmp_lt_u32_e32 vcc, s57, v0
	s_and_saveexec_b64 s[12:13], vcc
	s_xor_b64 s[52:53], exec, s[12:13]
	s_cbranch_execz .LBB0_1089
	v_and_b32_e32 v46, 7, v0
	v_lshlrev_b32_e32 v0, 4, v0
	v_and_b32_e32 v0, 0x7fffff80, v0
	v_lshlrev_b32_e32 v51, 7, v46
	v_add_u32_e32 v102, 0xffffdd00, v0
	v_or_b32_e32 v0, v51, v100
	v_lshlrev_b32_e32 v12, 2, v0
	v_or_b32_e32 v0, v102, v135
	v_lshlrev_b32_e32 v0, 13, v0
	v_mov_b32_e32 v1, v103
	v_lshl_add_u64 v[0:1], s[38:39], 0, v[0:1]
	v_lshlrev_b32_e32 v20, 8, v46
	v_mov_b32_e32 v21, v103
	s_load_dwordx4 s[12:15], s[30:31], 0x90
	s_load_dwordx2 s[54:55], s[30:31], 0xa8
	v_lshl_add_u64 v[0:1], v[0:1], 0, v[20:21]
	v_lshlrev_b32_e32 v22, 1, v100
	v_mov_b32_e32 v23, v103
	v_lshl_add_u64 v[0:1], v[0:1], 0, v[22:23]
	v_add_co_u32_e32 v0, vcc, s58, v0
	v_lshl_add_u64 v[24:25], v[102:103], 3, v[114:115]
	s_nop 0
	v_addc_co_u32_e32 v1, vcc, 0, v1, vcc
	global_load_dwordx4 v[16:19], v[0:1], off
	global_load_dwordx2 v[26:27], v[24:25], off
	s_waitcnt lgkmcnt(0)
	global_load_dwordx4 v[0:3], v12, s[12:13]
	global_load_dwordx4 v[4:7], v12, s[14:15]
	v_or_b32_e32 v8, v46, v128
	v_or_b32_e32 v9, v46, v130
	v_or_b32_e32 v10, v46, v132
	v_or_b32_e32 v11, v51, v166
	v_lshlrev_b32_e32 v30, 2, v8
	v_lshlrev_b32_e32 v31, 2, v9
	v_lshlrev_b32_e32 v33, 2, v10
	v_lshlrev_b32_e32 v29, 1, v11
	global_load_dwordx4 v[8:11], v12, s[12:13] offset:16
	s_nop 0
	global_load_dwordx4 v[12:15], v12, s[14:15] offset:16
	v_add_u32_e32 v28, v102, v101
	v_add_u32_e32 v32, v102, v129
	v_add_u32_e32 v36, v102, v131
	v_add_u32_e32 v38, v102, v133
	v_lshl_or_b32 v40, v28, 13, v29
	v_lshl_or_b32 v43, v32, 13, v29
	v_lshl_or_b32 v44, v36, 13, v29
	v_lshl_or_b32 v62, v38, 13, v29
	global_load_dwordx2 v[28:29], v[24:25], off offset:256
	global_load_dword v32, v30, s[54:55]
	s_nop 0
	global_load_dword v31, v31, s[54:55]
	s_nop 0
	global_load_dword v30, v33, s[54:55]
	v_or_b32_e32 v39, v102, v138
	v_mov_b32_e32 v35, v103
	v_mov_b32_e32 v37, v103
	v_or_b32_e32 v34, v46, v134
	v_lshlrev_b32_e32 v36, 13, v39
	v_lshl_add_u64 v[60:61], v[34:35], 2, s[54:55]
	v_lshl_add_u64 v[34:35], s[38:39], 0, v[36:37]
	v_lshl_add_u64 v[34:35], v[34:35], 0, v[20:21]
	v_lshl_add_u64 v[34:35], v[34:35], 0, v[22:23]
	v_add_co_u32_e32 v34, vcc, s58, v34
	global_load_ushort v66, v40, s[38:39] offset:2048
	global_load_ushort v67, v40, s[38:39] offset:2080
	global_load_ushort v68, v40, s[38:39] offset:2112
	global_load_ushort v52, v40, s[38:39] offset:2144
	global_load_ushort v49, v40, s[38:39] offset:2176
	global_load_ushort v42, v40, s[38:39] offset:2208
	global_load_ushort v38, v40, s[38:39] offset:2240
	global_load_ushort v33, v40, s[38:39] offset:2272
	v_addc_co_u32_e32 v35, vcc, 0, v35, vcc
	global_load_dwordx4 v[56:59], v[34:35], off
	global_load_ushort v69, v43, s[38:39] offset:2048
	global_load_ushort v70, v43, s[38:39] offset:2080
	global_load_ushort v71, v43, s[38:39] offset:2112
	global_load_ushort v55, v43, s[38:39] offset:2144
	global_load_ushort v50, v43, s[38:39] offset:2176
	global_load_ushort v45, v43, s[38:39] offset:2208
	global_load_ushort v41, v43, s[38:39] offset:2240
	global_load_ushort v35, v43, s[38:39] offset:2272
	global_load_ushort v72, v44, s[38:39] offset:2048
	global_load_ushort v73, v44, s[38:39] offset:2080
	global_load_ushort v74, v44, s[38:39] offset:2112
	global_load_ushort v53, v44, s[38:39] offset:2144
	global_load_ushort v47, v44, s[38:39] offset:2176
	global_load_ushort v43, v44, s[38:39] offset:2208
	global_load_ushort v39, v44, s[38:39] offset:2240
	global_load_ushort v36, v44, s[38:39] offset:2272
	global_load_dword v34, v[60:61], off
	s_waitcnt vmcnt(35)
	v_lshlrev_b32_e32 v37, 16, v16
	v_and_b32_e32 v16, 0xffff0000, v16
	s_waitcnt vmcnt(34)
	v_sub_f32_e32 v16, v16, v26
	v_sub_f32_e32 v37, v37, v26
	v_mul_f32_e32 v16, v27, v16
	v_mul_f32_e32 v37, v27, v37
	s_waitcnt vmcnt(32)
	v_fma_f32 v16, v1, v16, v5
	v_fma_f32 v37, v0, v37, v4
	v_cvt_pk_bf16_f32 v16, v16, s0
	v_cvt_pk_bf16_f32 v60, v37, s0
	global_load_ushort v75, v62, s[38:39] offset:2048
	global_load_ushort v76, v62, s[38:39] offset:2080
	global_load_ushort v77, v62, s[38:39] offset:2112
	global_load_ushort v54, v62, s[38:39] offset:2144
	global_load_ushort v48, v62, s[38:39] offset:2176
	global_load_ushort v44, v62, s[38:39] offset:2208
	global_load_ushort v40, v62, s[38:39] offset:2240
	global_load_ushort v37, v62, s[38:39] offset:2272
	ds_write_b16 v137, v16 offset:1296
	v_lshlrev_b32_e32 v16, 16, v17
	v_sub_f32_e32 v16, v16, v26
	v_mul_f32_e32 v16, v27, v16
	v_fma_f32 v16, v2, v16, v6
	v_cvt_pk_bf16_f32 v16, v16, s0
	ds_write_b16 v136, v16 offset:1568
	v_and_b32_e32 v16, 0xffff0000, v17
	v_sub_f32_e32 v16, v16, v26
	v_mul_f32_e32 v16, v27, v16
	v_fma_f32 v16, v3, v16, v7
	v_cvt_pk_bf16_f32 v16, v16, s0
	ds_write_b16 v137, v16 offset:1840
	v_lshlrev_b32_e32 v16, 16, v18
	v_sub_f32_e32 v16, v16, v26
	v_mul_f32_e32 v16, v27, v16
	s_waitcnt vmcnt(38)
; __device__ __forceinline__ bf16_t f2bf(float v) { return (bf16_t)(cvt_pk_bf16(v, 0.f) & 0xffffu); }
; __device__ __forceinline__ float bflo(unsigned w) { return __uint_as_float(w << 16); }
; __device__ __forceinline__ float bfhi(unsigned w) { return __uint_as_float(w & 0xffff0000u); }
; __device__ __forceinline__ void gmlp_item(KP P, int ch, int h, unsigned char* lds) {
;     ...
;     {
;         const int d0 = (t & 15) * 8;
;         float gg[8], bb[8];
; #pragma unroll
;         for (int j = 0; j < 8; ++j) { gg[j] = lng[h * 128 + d0 + j]; bb[j] = lnb[h * 128 + d0 + j]; }
; #pragma unroll
;         for (int i = 0; i < 4; ++i) {
;             const int s = (t >> 4) + 32 * i;
;             const u32x4 x = *(const u32x4*)(proj + (size_t)(r0 + s) * 4096 + 2048 + h * 128 + d0);
;             const f32x2 st = stats[s];
; #pragma unroll
;             for (int j = 0; j < 4; ++j) {
;                 T[(d0 + 2 * j) * 136 + s] = f2bf((bflo(x[j]) - st.x) * st.y * gg[2 * j] + bb[2 * j]);
;                 T[(d0 + 2 * j + 1) * 136 + s] = f2bf((bfhi(x[j]) - st.x) * st.y * gg[2 * j + 1] + bb[2 * j + 1]);
;             }
;         }
;     }
;     __syncthreads();
	v_fma_f32 v16, v8, v16, v12
	v_cvt_pk_bf16_f32 v78, v16, s0
	v_or_b32_e32 v16, v102, v139
	v_lshlrev_b32_e32 v16, 13, v16
	v_mov_b32_e32 v17, v103
	v_lshl_add_u64 v[16:17], s[38:39], 0, v[16:17]
	v_lshl_add_u64 v[16:17], v[16:17], 0, v[20:21]
	v_lshl_add_u64 v[16:17], v[16:17], 0, v[22:23]
	v_add_co_u32_e32 v16, vcc, s58, v16
	ds_write_b16 v136, v60 offset:1024
	s_nop 0
	v_addc_co_u32_e32 v17, vcc, 0, v17, vcc
	global_load_dwordx4 v[60:63], v[16:17], off
	global_load_dwordx2 v[64:65], v[24:25], off offset:512
	v_and_b32_e32 v16, 0xffff0000, v18
	v_sub_f32_e32 v16, v16, v26
	v_mul_f32_e32 v16, v27, v16
	v_fma_f32 v16, v9, v16, v13
	v_cvt_pk_bf16_f32 v16, v16, s0
	ds_write_b16 v137, v16 offset:2384
	v_lshlrev_b32_e32 v16, 16, v19
	v_sub_f32_e32 v16, v16, v26
	v_mul_f32_e32 v16, v27, v16
	v_fma_f32 v16, v10, v16, v14
	v_cvt_pk_bf16_f32 v16, v16, s0
	ds_write_b16 v136, v16 offset:2656
	v_and_b32_e32 v16, 0xffff0000, v19
	v_sub_f32_e32 v16, v16, v26
	v_mul_f32_e32 v16, v27, v16
	v_fma_f32 v16, v11, v16, v15
	v_cvt_pk_bf16_f32 v16, v16, s0
	ds_write_b16 v137, v16 offset:2928
	s_waitcnt vmcnt(27)
	v_lshlrev_b32_e32 v16, 16, v56
	v_sub_f32_e32 v16, v16, v28
	v_mul_f32_e32 v16, v29, v16
	v_fma_f32 v16, v0, v16, v4
	v_cvt_pk_bf16_f32 v16, v16, s0
	ds_write_b16 v136, v16 offset:1088
	v_and_b32_e32 v16, 0xffff0000, v56
	v_sub_f32_e32 v16, v16, v28
	v_mul_f32_e32 v16, v29, v16
	v_fma_f32 v16, v1, v16, v5
	v_cvt_pk_bf16_f32 v16, v16, s0
	ds_write_b16 v137, v16 offset:1360
	v_lshlrev_b32_e32 v16, 16, v57
	v_sub_f32_e32 v16, v16, v28
	v_mul_f32_e32 v16, v29, v16
	v_fma_f32 v16, v2, v16, v6
	v_cvt_pk_bf16_f32 v26, v16, s0
	v_add_lshl_u32 v16, v102, v140, 13
	v_mov_b32_e32 v17, v103
	v_lshl_add_u64 v[16:17], s[38:39], 0, v[16:17]
	v_lshl_add_u64 v[16:17], v[16:17], 0, v[20:21]
	v_lshl_add_u64 v[16:17], v[16:17], 0, v[22:23]
	v_add_co_u32_e32 v16, vcc, s58, v16
	global_load_dwordx2 v[24:25], v[24:25], off offset:768
	s_nop 0
	v_addc_co_u32_e32 v17, vcc, 0, v17, vcc
	global_load_dwordx4 v[16:19], v[16:17], off
	v_and_b32_e32 v20, 0xffff0000, v57
	v_sub_f32_e32 v20, v20, v28
	v_mul_f32_e32 v20, v29, v20
	v_fma_f32 v20, v3, v20, v7
	v_cvt_pk_bf16_f32 v20, v20, s0
	ds_write_b16 v137, v20 offset:1904
	v_lshlrev_b32_e32 v20, 16, v58
	v_sub_f32_e32 v20, v20, v28
	v_mul_f32_e32 v20, v29, v20
	v_fma_f32 v20, v8, v20, v12
	v_cvt_pk_bf16_f32 v20, v20, s0
	ds_write_b16 v136, v20 offset:2176
	v_and_b32_e32 v20, 0xffff0000, v58
	v_sub_f32_e32 v20, v20, v28
	v_mul_f32_e32 v20, v29, v20
	v_fma_f32 v20, v9, v20, v13
	v_cvt_pk_bf16_f32 v20, v20, s0
	ds_write_b16 v137, v20 offset:2448
	v_lshlrev_b32_e32 v20, 16, v59
	v_sub_f32_e32 v20, v20, v28
	v_mul_f32_e32 v20, v29, v20
	v_fma_f32 v20, v10, v20, v14
	v_cvt_pk_bf16_f32 v20, v20, s0
	ds_write_b16 v136, v20 offset:2720
	v_and_b32_e32 v20, 0xffff0000, v59
	v_sub_f32_e32 v20, v20, v28
	v_mul_f32_e32 v20, v29, v20
	v_fma_f32 v20, v11, v20, v15
	v_cvt_pk_bf16_f32 v20, v20, s0
	ds_write_b16 v137, v20 offset:2992
	ds_write_b16 v136, v78 offset:2112
	ds_write_b16 v136, v26 offset:1632
	s_waitcnt vmcnt(3)
	v_lshlrev_b32_e32 v20, 16, v60
	s_waitcnt vmcnt(2)
	v_sub_f32_e32 v20, v20, v64
	v_mul_f32_e32 v20, v65, v20
	v_fma_f32 v20, v0, v20, v4
	v_cvt_pk_bf16_f32 v20, v20, s0
	ds_write_b16 v136, v20 offset:1152
	v_and_b32_e32 v20, 0xffff0000, v60
	v_sub_f32_e32 v20, v20, v64
	v_mul_f32_e32 v20, v65, v20
	v_fma_f32 v20, v1, v20, v5
	v_cvt_pk_bf16_f32 v20, v20, s0
	ds_write_b16 v137, v20 offset:1424
	v_lshlrev_b32_e32 v20, 16, v61
	v_sub_f32_e32 v20, v20, v64
	v_mul_f32_e32 v20, v65, v20
	v_fma_f32 v20, v2, v20, v6
	v_cvt_pk_bf16_f32 v20, v20, s0
	ds_write_b16 v136, v20 offset:1696
	v_and_b32_e32 v20, 0xffff0000, v61
	v_sub_f32_e32 v20, v20, v64
	v_mul_f32_e32 v20, v65, v20
	v_fma_f32 v20, v3, v20, v7
	v_cvt_pk_bf16_f32 v20, v20, s0
	ds_write_b16 v137, v20 offset:1968
	v_lshlrev_b32_e32 v20, 16, v62
	v_sub_f32_e32 v20, v20, v64
	v_mul_f32_e32 v20, v65, v20
	v_fma_f32 v20, v8, v20, v12
	v_cvt_pk_bf16_f32 v20, v20, s0
	ds_write_b16 v136, v20 offset:2240
	v_and_b32_e32 v20, 0xffff0000, v62
	v_sub_f32_e32 v20, v20, v64
	v_mul_f32_e32 v20, v65, v20
	v_fma_f32 v20, v9, v20, v13
	v_cvt_pk_bf16_f32 v20, v20, s0
	ds_write_b16 v137, v20 offset:2512
	v_lshlrev_b32_e32 v20, 16, v63
	v_sub_f32_e32 v20, v20, v64
	v_mul_f32_e32 v20, v65, v20
	v_fma_f32 v20, v10, v20, v14
	v_cvt_pk_bf16_f32 v20, v20, s0
	ds_write_b16 v136, v20 offset:2784
	v_and_b32_e32 v20, 0xffff0000, v63
	v_sub_f32_e32 v20, v20, v64
	v_mul_f32_e32 v20, v65, v20
	v_fma_f32 v20, v11, v20, v15
	v_cvt_pk_bf16_f32 v20, v20, s0
	ds_write_b16 v137, v20 offset:3056
	s_waitcnt vmcnt(0)
	v_lshlrev_b32_e32 v20, 16, v16
	v_sub_f32_e32 v20, v20, v24
	v_mul_f32_e32 v20, v25, v20
	v_fma_f32 v0, v0, v20, v4
	v_cvt_pk_bf16_f32 v0, v0, s0
	ds_write_b16 v136, v0 offset:1216
	v_and_b32_e32 v0, 0xffff0000, v16
	v_sub_f32_e32 v0, v0, v24
	v_mul_f32_e32 v0, v25, v0
	v_fma_f32 v0, v1, v0, v5
	v_cvt_pk_bf16_f32 v0, v0, s0
	ds_write_b16 v137, v0 offset:1488
	v_lshlrev_b32_e32 v0, 16, v17
	v_sub_f32_e32 v0, v0, v24
	v_mul_f32_e32 v0, v25, v0
	v_fma_f32 v0, v2, v0, v6
	v_cvt_pk_bf16_f32 v0, v0, s0
	ds_write_b16 v136, v0 offset:1760
	v_and_b32_e32 v0, 0xffff0000, v17
	v_sub_f32_e32 v0, v0, v24
	v_mul_f32_e32 v0, v25, v0
	v_fmac_f32_e32 v7, v3, v0
	v_cvt_pk_bf16_f32 v0, v7, s0
	ds_write_b16 v137, v0 offset:2032
	v_lshlrev_b32_e32 v0, 16, v18
	v_sub_f32_e32 v0, v0, v24
	v_mul_f32_e32 v0, v25, v0
	v_fma_f32 v0, v8, v0, v12
	v_cvt_pk_bf16_f32 v0, v0, s0
	ds_write_b16 v136, v0 offset:2304
	v_and_b32_e32 v0, 0xffff0000, v18
	v_sub_f32_e32 v0, v0, v24
	v_mul_f32_e32 v0, v25, v0
	v_fma_f32 v0, v9, v0, v13
	v_cvt_pk_bf16_f32 v0, v0, s0
	ds_write_b16 v137, v0 offset:2576
	v_lshlrev_b32_e32 v0, 16, v19
	v_sub_f32_e32 v0, v0, v24
	v_mul_f32_e32 v0, v25, v0
	v_fma_f32 v0, v10, v0, v14
	v_cvt_pk_bf16_f32 v0, v0, s0
	ds_write_b16 v136, v0 offset:2848
	v_and_b32_e32 v0, 0xffff0000, v19
	v_sub_f32_e32 v0, v0, v24
	v_mul_f32_e32 v0, v25, v0
	v_fmac_f32_e32 v15, v11, v0
	v_cvt_pk_bf16_f32 v0, v15, s0
	ds_write_b16 v137, v0 offset:3120
	v_add_lshl_u32 v0, v51, v141, 8
	v_mov_b32_e32 v1, v103
	v_lshl_add_u64 v[24:25], v[104:105], 0, v[0:1]
	s_waitcnt lgkmcnt(0)
	s_barrier
; __device__ __forceinline__ bf16_t f2bf(float v) { return (bf16_t)(cvt_pk_bf16(v, 0.f) & 0xffffu); }
; __device__ __forceinline__ float bf2f(bf16_t b) { return __uint_as_float(((unsigned)b) << 16); }
; __device__ __forceinline__ size_t tl(int r, int c, int K) { return ((size_t)(r >> 8) * (size_t)(K >> 6) + (size_t)(c >> 6)) * 16384 + (size_t)((r & 255) << 6) + (size_t)(c & 63); }
; #define MFMA16(a, b, c) __builtin_amdgcn_mfma_f32_16x16x32_bf16((a), (b), (c), 0, 0, 0)
; __device__ __forceinline__ void gmlp_item(KP P, int ch, int h, unsigned char* lds) {
;     ...
;     {
;         const int q = lane >> 4, l15 = lane & 15;
;         bf16x8 Wa[4];
; #pragma unroll
;         for (int ks = 0; ks < 4; ++ks) Wa[ks] = *(const bf16x8*)(Wsb + ((size_t)h * 128 + 16 * w + l15) * 128 + ks * 32 + 8 * q);
; #pragma unroll
;         for (int db = 0; db < 8; ++db) {
;             f32x4 acc = (f32x4){0.f, 0.f, 0.f, 0.f};
; #pragma unroll
;             for (int ks = 0; ks < 4; ++ks) acc = MFMA16(Wa[ks], *(const bf16x8*)(T + (db * 16 + l15) * 136 + ks * 32 + 8 * q), acc);
; #pragma unroll
;             for (int reg = 0; reg < 4; ++reg) {
;                 const int tt = 16 * w + q * 4 + reg, c = h * 128 + db * 16 + l15;
;                 gm[tl(r0 + tt, c, 1024)] = f2bf(bf2f(uu16[db][reg]) * (acc[reg] + bsv[reg]));
;             }
;         }
	global_load_dwordx4 v[12:15], v[24:25], off
	global_load_dwordx4 v[0:3], v[24:25], off offset:64
	ds_read_b128 v[8:11], v152 offset:1024
	ds_read_b128 v[16:19], v152 offset:1088
	global_load_dwordx4 v[4:7], v[24:25], off offset:128
	v_mov_b32_e32 v29, v103
	v_lshlrev_b32_e32 v60, 1, v166
	v_mov_b32_e32 v61, v103
	s_waitcnt vmcnt(2) lgkmcnt(1)
	v_mfma_f32_16x16x32_bf16 v[20:23], v[12:15], v[8:11], 0
	global_load_dwordx4 v[8:11], v[24:25], off offset:192
	s_waitcnt vmcnt(2) lgkmcnt(0)
	v_mfma_f32_16x16x32_bf16 v[16:19], v[0:3], v[16:19], v[20:23]
	s_nop 4
	ds_read_b128 v[20:23], v152 offset:1152
	ds_read_b128 v[24:27], v152 offset:1216
	ds_read_b128 v[56:59], v152 offset:5504
	s_waitcnt vmcnt(1) lgkmcnt(2)
	v_mfma_f32_16x16x32_bf16 v[16:19], v[4:7], v[20:23], v[16:19]
	v_add_u32_e32 v22, v142, v102
	v_lshlrev_b32_e32 v20, 16, v66
	s_waitcnt vmcnt(0) lgkmcnt(1)
	v_mfma_f32_16x16x32_bf16 v[16:19], v[8:11], v[24:27], v[16:19]
	ds_read_b128 v[24:27], v152 offset:5440
	s_nop 6
	v_add_f32_e32 v16, v32, v16
	v_mul_f32_e32 v16, v16, v20
	v_lshlrev_b32_e32 v20, 11, v22
	v_and_b32_e32 v20, 0x3f80000, v20
	v_lshl_or_b32 v102, v46, 16, v20
	v_lshlrev_b32_e32 v22, 7, v22
	v_lshl_add_u64 v[20:21], s[40:41], 0, v[102:103]
	v_and_b32_e32 v28, 0x7e00, v22
	v_lshl_add_u64 v[20:21], v[20:21], 0, v[28:29]
	v_lshl_add_u64 v[62:63], v[20:21], 0, v[60:61]
	ds_read_b128 v[20:23], v152 offset:5376
	v_cvt_pk_bf16_f32 v16, v16, s0
	s_waitcnt lgkmcnt(0)
	v_mfma_f32_16x16x32_bf16 v[20:23], v[12:15], v[20:23], 0
	global_store_short v[62:63], v16, off
	v_lshlrev_b32_e32 v16, 16, v69
	v_add_f32_e32 v17, v31, v17
	v_mul_f32_e32 v16, v17, v16
	v_cvt_pk_bf16_f32 v16, v16, s0
	global_store_short v[62:63], v16, off offset:128
	v_lshlrev_b32_e32 v16, 16, v72
	v_add_f32_e32 v17, v30, v18
	v_mfma_f32_16x16x32_bf16 v[20:23], v[0:3], v[24:27], v[20:23]
	v_mul_f32_e32 v16, v17, v16
	v_cvt_pk_bf16_f32 v16, v16, s0
	global_store_short v[62:63], v16, off offset:256
	v_add_f32_e32 v25, v34, v19
	ds_read_b128 v[16:19], v152 offset:5568
	v_mfma_f32_16x16x32_bf16 v[20:23], v[4:7], v[56:59], v[20:23]
	v_lshlrev_b32_e32 v24, 16, v75
	v_mul_f32_e32 v24, v25, v24
	v_cvt_pk_bf16_f32 v24, v24, s0
	s_waitcnt lgkmcnt(0)
	v_mfma_f32_16x16x32_bf16 v[16:19], v[8:11], v[16:19], v[20:23]
	global_store_short v[62:63], v24, off offset:384
	ds_read_b128 v[24:27], v152 offset:9792
	ds_read_b128 v[56:59], v152 offset:9856
	v_lshlrev_b32_e32 v20, 16, v67
	v_or_b32_e32 v102, 0x8000, v102
	s_nop 2
	v_add_f32_e32 v16, v32, v16
	v_mul_f32_e32 v16, v16, v20
	ds_read_b128 v[20:23], v152 offset:9728
	v_cvt_pk_bf16_f32 v16, v16, s0
	s_waitcnt lgkmcnt(0)
	v_mfma_f32_16x16x32_bf16 v[20:23], v[12:15], v[20:23], 0
	global_store_short v[62:63], v16, off offset:32
	v_lshlrev_b32_e32 v16, 16, v70
	v_add_f32_e32 v17, v31, v17
	v_mul_f32_e32 v16, v17, v16
	v_cvt_pk_bf16_f32 v16, v16, s0
	global_store_short v[62:63], v16, off offset:160
	v_lshlrev_b32_e32 v16, 16, v73
	v_add_f32_e32 v17, v30, v18
	v_mfma_f32_16x16x32_bf16 v[20:23], v[0:3], v[24:27], v[20:23]
	v_mul_f32_e32 v16, v17, v16
	v_cvt_pk_bf16_f32 v16, v16, s0
	global_store_short v[62:63], v16, off offset:288
	v_add_f32_e32 v25, v34, v19
	ds_read_b128 v[16:19], v152 offset:9920
	v_mfma_f32_16x16x32_bf16 v[20:23], v[4:7], v[56:59], v[20:23]
	v_lshlrev_b32_e32 v24, 16, v76
	v_mul_f32_e32 v24, v25, v24
	v_cvt_pk_bf16_f32 v24, v24, s0
	s_waitcnt lgkmcnt(0)
	v_mfma_f32_16x16x32_bf16 v[16:19], v[8:11], v[16:19], v[20:23]
	global_store_short v[62:63], v24, off offset:416
	ds_read_b128 v[24:27], v152 offset:14144
	ds_read_b128 v[56:59], v152 offset:14208
	v_lshlrev_b32_e32 v20, 16, v68
	s_nop 3
	v_add_f32_e32 v16, v32, v16
	v_mul_f32_e32 v16, v16, v20
	ds_read_b128 v[20:23], v152 offset:14080
	v_cvt_pk_bf16_f32 v16, v16, s0
	s_waitcnt lgkmcnt(0)
	v_mfma_f32_16x16x32_bf16 v[20:23], v[12:15], v[20:23], 0
	global_store_short v[62:63], v16, off offset:64
	v_lshlrev_b32_e32 v16, 16, v71
	v_add_f32_e32 v17, v31, v17
	v_mul_f32_e32 v16, v17, v16
	v_cvt_pk_bf16_f32 v16, v16, s0
	global_store_short v[62:63], v16, off offset:192
	v_lshlrev_b32_e32 v16, 16, v74
	v_add_f32_e32 v17, v30, v18
	v_mfma_f32_16x16x32_bf16 v[20:23], v[0:3], v[24:27], v[20:23]
	v_mul_f32_e32 v16, v17, v16
	v_cvt_pk_bf16_f32 v16, v16, s0
	global_store_short v[62:63], v16, off offset:320
	v_add_f32_e32 v25, v34, v19
	ds_read_b128 v[16:19], v152 offset:14272
	v_mfma_f32_16x16x32_bf16 v[20:23], v[4:7], v[56:59], v[20:23]
	v_lshlrev_b32_e32 v24, 16, v77
	v_mul_f32_e32 v24, v25, v24
	v_cvt_pk_bf16_f32 v24, v24, s0
	s_waitcnt lgkmcnt(0)
	v_mfma_f32_16x16x32_bf16 v[16:19], v[8:11], v[16:19], v[20:23]
	global_store_short v[62:63], v24, off offset:448
	ds_read_b128 v[24:27], v152 offset:18496
	ds_read_b128 v[56:59], v152 offset:18560
	v_lshlrev_b32_e32 v20, 16, v52
	s_nop 3
	v_add_f32_e32 v16, v32, v16
	v_mul_f32_e32 v16, v16, v20
	ds_read_b128 v[20:23], v152 offset:18432
	v_cvt_pk_bf16_f32 v16, v16, s0
	s_waitcnt lgkmcnt(0)
; __device__ __forceinline__ bf16_t f2bf(float v) { return (bf16_t)(cvt_pk_bf16(v, 0.f) & 0xffffu); }
; __device__ __forceinline__ float bf2f(bf16_t b) { return __uint_as_float(((unsigned)b) << 16); }
; __device__ __forceinline__ size_t tl(int r, int c, int K) { return ((size_t)(r >> 8) * (size_t)(K >> 6) + (size_t)(c >> 6)) * 16384 + (size_t)((r & 255) << 6) + (size_t)(c & 63); }
; #define MFMA16(a, b, c) __builtin_amdgcn_mfma_f32_16x16x32_bf16((a), (b), (c), 0, 0, 0)
; __device__ __forceinline__ void gmlp_item(KP P, int ch, int h, unsigned char* lds) {
;     ...
; #pragma unroll
;         for (int db = 0; db < 8; ++db) {
;             f32x4 acc = (f32x4){0.f, 0.f, 0.f, 0.f};
; #pragma unroll
;             for (int ks = 0; ks < 4; ++ks) acc = MFMA16(Wa[ks], *(const bf16x8*)(T + (db * 16 + l15) * 136 + ks * 32 + 8 * q), acc);
; #pragma unroll
;             for (int reg = 0; reg < 4; ++reg) {
;                 const int tt = 16 * w + q * 4 + reg, c = h * 128 + db * 16 + l15;
;                 gm[tl(r0 + tt, c, 1024)] = f2bf(bf2f(uu16[db][reg]) * (acc[reg] + bsv[reg]));
;             }
;         }
;     }
;     __syncthreads();
	v_mfma_f32_16x16x32_bf16 v[20:23], v[12:15], v[20:23], 0
	global_store_short v[62:63], v16, off offset:96
	v_lshlrev_b32_e32 v16, 16, v55
	v_add_f32_e32 v17, v31, v17
	v_mul_f32_e32 v16, v17, v16
	v_cvt_pk_bf16_f32 v16, v16, s0
	global_store_short v[62:63], v16, off offset:224
	v_lshlrev_b32_e32 v16, 16, v53
	v_add_f32_e32 v17, v30, v18
	v_mfma_f32_16x16x32_bf16 v[20:23], v[0:3], v[24:27], v[20:23]
	v_mul_f32_e32 v16, v17, v16
	v_cvt_pk_bf16_f32 v16, v16, s0
	global_store_short v[62:63], v16, off offset:352
	v_add_f32_e32 v25, v34, v19
	ds_read_b128 v[16:19], v152 offset:18624
	v_mfma_f32_16x16x32_bf16 v[20:23], v[4:7], v[56:59], v[20:23]
	v_lshlrev_b32_e32 v24, 16, v54
	v_mul_f32_e32 v24, v25, v24
	v_cvt_pk_bf16_f32 v24, v24, s0
	s_waitcnt lgkmcnt(0)
	v_mfma_f32_16x16x32_bf16 v[16:19], v[8:11], v[16:19], v[20:23]
	global_store_short v[62:63], v24, off offset:480
	ds_read_b128 v[24:27], v152 offset:22848
	s_nop 0
	v_lshlrev_b32_e32 v20, 16, v49
	s_nop 3
	v_add_f32_e32 v16, v32, v16
	v_mul_f32_e32 v16, v16, v20
	v_lshl_add_u64 v[20:21], s[40:41], 0, v[102:103]
	v_lshl_add_u64 v[20:21], v[20:21], 0, v[28:29]
	v_lshl_add_u64 v[28:29], v[20:21], 0, v[60:61]
	ds_read_b128 v[20:23], v152 offset:22784
	v_cvt_pk_bf16_f32 v16, v16, s0
	s_waitcnt lgkmcnt(0)
	v_mfma_f32_16x16x32_bf16 v[20:23], v[12:15], v[20:23], 0
	global_store_short v[28:29], v16, off
	v_lshlrev_b32_e32 v16, 16, v50
	v_add_f32_e32 v17, v31, v17
	v_mul_f32_e32 v16, v17, v16
	v_cvt_pk_bf16_f32 v16, v16, s0
	ds_read_b128 v[50:53], v152 offset:22912
	global_store_short v[28:29], v16, off offset:128
	v_lshlrev_b32_e32 v16, 16, v47
	v_add_f32_e32 v17, v30, v18
	v_mfma_f32_16x16x32_bf16 v[20:23], v[0:3], v[24:27], v[20:23]
	v_mul_f32_e32 v16, v17, v16
	v_cvt_pk_bf16_f32 v16, v16, s0
	global_store_short v[28:29], v16, off offset:256
	v_add_f32_e32 v25, v34, v19
	ds_read_b128 v[16:19], v152 offset:22976
	s_waitcnt lgkmcnt(1)
	v_mfma_f32_16x16x32_bf16 v[20:23], v[4:7], v[50:53], v[20:23]
	v_lshlrev_b32_e32 v24, 16, v48
	v_mul_f32_e32 v24, v25, v24
	v_cvt_pk_bf16_f32 v24, v24, s0
	s_waitcnt lgkmcnt(0)
	v_mfma_f32_16x16x32_bf16 v[16:19], v[8:11], v[16:19], v[20:23]
	global_store_short v[28:29], v24, off offset:384
	ds_read_b128 v[24:27], v152 offset:27200
	ds_read_b128 v[46:49], v152 offset:27264
	v_lshlrev_b32_e32 v20, 16, v42
	s_nop 3
	v_add_f32_e32 v16, v32, v16
	v_mul_f32_e32 v16, v16, v20
	ds_read_b128 v[20:23], v152 offset:27136
	v_cvt_pk_bf16_f32 v16, v16, s0
	s_waitcnt lgkmcnt(0)
	v_mfma_f32_16x16x32_bf16 v[20:23], v[12:15], v[20:23], 0
	global_store_short v[28:29], v16, off offset:32
	v_lshlrev_b32_e32 v16, 16, v45
	v_add_f32_e32 v17, v31, v17
	v_mul_f32_e32 v16, v17, v16
	v_cvt_pk_bf16_f32 v16, v16, s0
	global_store_short v[28:29], v16, off offset:160
	v_lshlrev_b32_e32 v16, 16, v43
	v_add_f32_e32 v17, v30, v18
	v_mfma_f32_16x16x32_bf16 v[20:23], v[0:3], v[24:27], v[20:23]
	v_mul_f32_e32 v16, v17, v16
	v_cvt_pk_bf16_f32 v16, v16, s0
	global_store_short v[28:29], v16, off offset:288
	v_add_f32_e32 v25, v34, v19
	ds_read_b128 v[16:19], v152 offset:27328
	v_mfma_f32_16x16x32_bf16 v[20:23], v[4:7], v[46:49], v[20:23]
	v_lshlrev_b32_e32 v24, 16, v44
	v_mul_f32_e32 v24, v25, v24
	v_cvt_pk_bf16_f32 v24, v24, s0
	s_waitcnt lgkmcnt(0)
	v_mfma_f32_16x16x32_bf16 v[16:19], v[8:11], v[16:19], v[20:23]
	global_store_short v[28:29], v24, off offset:416
	ds_read_b128 v[24:27], v152 offset:31552
	s_nop 0
	v_lshlrev_b32_e32 v20, 16, v38
	s_nop 3
	v_add_f32_e32 v16, v32, v16
	v_mul_f32_e32 v16, v16, v20
	ds_read_b128 v[20:23], v152 offset:31488
	s_waitcnt lgkmcnt(0)
	v_mfma_f32_16x16x32_bf16 v[12:15], v[12:15], v[20:23], 0
	ds_read_b128 v[20:23], v152 offset:31616
	v_cvt_pk_bf16_f32 v16, v16, s0
	global_store_short v[28:29], v16, off offset:64
	v_mfma_f32_16x16x32_bf16 v[0:3], v[0:3], v[24:27], v[12:15]
	v_lshlrev_b32_e32 v16, 16, v41
	v_add_f32_e32 v17, v31, v17
	v_mul_f32_e32 v16, v17, v16
	s_nop 0
	ds_read_b128 v[12:15], v152 offset:31680
	s_waitcnt lgkmcnt(1)
	v_mfma_f32_16x16x32_bf16 v[0:3], v[4:7], v[20:23], v[0:3]
	v_cvt_pk_bf16_f32 v16, v16, s0
	global_store_short v[28:29], v16, off offset:192
	v_lshlrev_b32_e32 v16, 16, v39
	v_add_f32_e32 v17, v30, v18
	v_mul_f32_e32 v16, v17, v16
	v_cvt_pk_bf16_f32 v16, v16, s0
	s_waitcnt lgkmcnt(0)
	v_mfma_f32_16x16x32_bf16 v[0:3], v[8:11], v[12:15], v[0:3]
	global_store_short v[28:29], v16, off offset:320
	v_lshlrev_b32_e32 v16, 16, v40
	v_add_f32_e32 v17, v34, v19
	v_mul_f32_e32 v4, v17, v16
	v_cvt_pk_bf16_f32 v4, v4, s0
	global_store_short v[28:29], v4, off offset:448
	v_lshlrev_b32_e32 v4, 16, v33
	s_nop 0
	v_add_f32_e32 v0, v32, v0
	v_mul_f32_e32 v0, v0, v4
	v_cvt_pk_bf16_f32 v0, v0, s0
	global_store_short v[28:29], v0, off offset:96
	v_lshlrev_b32_e32 v0, 16, v35
	v_add_f32_e32 v1, v31, v1
	v_mul_f32_e32 v0, v1, v0
	v_cvt_pk_bf16_f32 v0, v0, s0
	global_store_short v[28:29], v0, off offset:224
	v_lshlrev_b32_e32 v0, 16, v36
	v_add_f32_e32 v1, v30, v2
	v_mul_f32_e32 v0, v1, v0
	v_cvt_pk_bf16_f32 v0, v0, s0
	global_store_short v[28:29], v0, off offset:352
	v_lshlrev_b32_e32 v0, 16, v37
	v_add_f32_e32 v1, v34, v3
	v_mul_f32_e32 v0, v1, v0
	v_cvt_pk_bf16_f32 v0, v0, s0
	global_store_short v[28:29], v0, off offset:480
	s_barrier

; __device__ __forceinline__ void ssm_out_item(KP P, int g, int cbase, unsigned char* lds) {
;     const bf16_t* proj = (const bf16_t*)(P->ws + OFF_RA); const bf16_t* Hc = (const bf16_t*)(P->ws + OFF_HC);
;     const int tid = threadIdx.x, wid = tid >> 6, lane = tid & 63, cb = cbase + wid;
;     const bf16x8* AK = (const bf16x8*)(P->ws + OFF_AK) + (((long)g * 63 - ((lane >> 4) >> 1)) * 16 + (lane & 15)) * 2 + ((lane >> 4) & 1);
;     const u32x4* AG = (const u32x4*)(P->ws + OFF_AG) + (size_t)g * 256 * 64 + lane;
;     bf16_t* ya = (bf16_t*)(P->ws + OFF_RB);
;     u32x4* stage = (u32x4*)lds;
;     const int n = cb * 16 + (lane & 15), q = lane >> 4;
;     const bf16_t* xbase = proj + (size_t)(n * 32 + (q >> 1)) * 4096 + g * 16 + 8 * (q & 1);
;     bf16x8 X[16], H[8];
; #pragma unroll
;     for (int i = 0; i < 16; ++i) X[i] = *(const bf16x8*)(xbase + (size_t)(2 * i) * 4096);
; #pragma unroll
;     for (int j = 0; j < 8; ++j) H[j] = *(const bf16x8*)(Hc + ((size_t)n * 64 + g) * 256 + j * 32 + 8 * q);
; __global__ void __launch_bounds__(512, 2) mega(Params Parg) {
;     ...
;         for (int it = blk; it < 256; it += G) ssm_out_item(P, it >> 2, (it & 3) * 8, shm);
.LBB0_1150:
	s_or_b64 exec, exec, s[6:7]
	s_waitcnt lgkmcnt(0)
	s_barrier
	s_mov_b64 s[6:7], s[0:1]
	v_mov_b32_e32 v0, v204
	s_andn2_b64 vcc, exec, s[10:11]
	s_cbranch_vccnz .LBB0_1153
	s_load_dwordx2 s[8:9], s[6:7], 0x118
	v_mov_b32_e32 v171, 0
	v_lshlrev_b32_e32 v170, 4, v96
	v_bfe_u32 v3, v96, 4, 1
	s_mov_b64 s[10:11], 0x1c4c0000
	s_waitcnt lgkmcnt(0)
	v_lshl_add_u64 v[0:1], s[8:9], 0, v[170:171]
	v_lshlrev_b32_e32 v170, 5, v166
	v_lshl_add_u64 v[4:5], s[8:9], 0, v[170:171]
	v_lshlrev_b32_e32 v170, 4, v3
	v_lshl_add_u64 v[4:5], v[4:5], 0, v[170:171]
	v_lshlrev_b32_e32 v170, 1, v98
	s_add_u32 s6, s8, 0xc8c0000
	v_lshl_add_u64 v[172:173], v[4:5], 0, s[10:11]
	v_lshl_add_u64 v[4:5], s[8:9], 0, v[170:171]
	s_mov_b64 s[10:11], 0x194c0000
	v_lshlrev_b32_e32 v170, 10, v164
	s_addc_u32 s7, s9, 0
	v_lshl_add_u64 v[174:175], v[4:5], 0, s[10:11]
	v_lshl_add_u64 v[0:1], v[170:171], 4, v[0:1]
	s_mov_b64 s[10:11], 0x1b4c0000
	v_lshlrev_b32_e32 v2, 3, v3
	s_add_u32 s8, s8, 0x4840000
	v_lshl_add_u64 v[176:177], v[0:1], 0, s[10:11]
	v_lshlrev_b32_e32 v0, 12, v166
	v_lshrrev_b32_e32 v168, 5, v96
	s_addc_u32 s9, s9, 0
	v_lshlrev_b32_e32 v169, 2, v97
	v_lshlrev_b32_e32 v178, 1, v2
	v_mov_b32_e32 v179, v171
	s_movk_i32 s18, 0x4000
	s_mov_b32 s19, 0x8000
	s_mov_b32 s25, 0xc000
	s_mov_b32 s30, 0x10000
	s_mov_b32 s31, 0x14000
	s_mov_b32 s34, 0x18000
	s_mov_b32 s35, 0x1c000
	s_mov_b32 s36, 0x20000
	s_mov_b32 s37, 0x24000
	s_mov_b32 s38, 0x28000
	s_mov_b32 s39, 0x2c000
	s_mov_b32 s40, 0x30000
	s_mov_b32 s41, 0x34000
	s_mov_b32 s42, 0x38000
	s_mov_b32 s43, 0x3c000
	s_movk_i32 s44, 0x1000
	s_movk_i32 s45, 0x2000
	s_movk_i32 s46, 0x3000
	s_movk_i32 s47, 0x7000
	v_and_b32_e32 v180, 0x7000, v0
	v_mov_b32_e32 v181, v171
	s_movk_i32 s48, 0x5000
	s_mov_b32 s49, 0x21000
	s_movk_i32 s50, 0x6000
	s_mov_b32 s51, 0x22000
	s_mov_b32 s52, 0x23000
	s_mov_b32 s54, s2
	s_cmpk_lg_i32 s20, 0x100
	s_cbranch_scc1 .Lmy_noperm7
	s_and_b32 s10, s2, 7
	s_lshr_b32 s54, s2, 3
	s_and_b32 s53, s54, 15
	s_lshr_b32 s54, s54, 4
	s_lshl_b32 s54, s54, 3
	s_or_b32 s54, s54, s10
	s_lshl_b32 s54, s54, 4
	s_or_b32 s54, s54, s53
.Lmy_noperm7:
	s_lshl_b32 s53, s54, 3
